# stack as v106 with the gate-pass waits of the first eight row-blocks unconditional (vmcnt(15-k) is exact for the ratio passes and forces only loads in the storing passes)
# speedup vs baseline: 1.0072x; 1.0026x over previous
.LBB0_762:
	v_cndmask_b32_e64 v3, 0, 1, s[36:37]
	v_or_b32_e32 v158, 0x80, v4
	s_waitcnt vmcnt(14)
	v_cvt_f32_ubyte1_e32 v233, v226
	v_cvt_f32_ubyte0_e32 v232, v226
	v_cvt_f32_ubyte3_e32 v235, v226
	v_cvt_f32_ubyte2_e32 v234, v226
	v_cvt_f32_ubyte1_e32 v229, v227
	v_cvt_f32_ubyte0_e32 v228, v227
	v_cvt_f32_ubyte3_e32 v231, v227
	v_cvt_f32_ubyte2_e32 v230, v227
	s_mov_b64 s[30:31], -1
	s_and_b64 vcc, exec, s[12:13]
	v_cmp_ne_u32_e64 s[14:15], 1, v3
	s_cbranch_vccnz .LBB0_768
	v_mul_f32_e32 v159, 0x3b808081, v234
	v_mul_f32_e32 v189, v100, v159
	v_mul_f32_e32 v159, 0x3b808081, v230
	v_mul_f32_e32 v3, 0x3b808081, v232
	v_mul_f32_e32 v157, 0x3b808081, v233
	v_mul_f32_e32 v169, v96, v159
	v_mul_f32_e32 v159, 0x3b808081, v235
	v_mul_f32_e32 v149, v98, v3
	v_mul_f32_e32 v3, 0x3b808081, v228
	v_mul_f32_e32 v179, v99, v157
	v_mul_f32_e32 v157, 0x3b808081, v229
	v_mul_f32_e32 v213, v101, v159
	v_mul_f32_e32 v159, 0x3b808081, v231
	v_mul_f32_e32 v3, v94, v3
	v_mul_f32_e32 v157, v95, v157
	v_mul_f32_e32 v203, v97, v159
	s_and_b64 vcc, exec, s[14:15]
	v_lshlrev_b64 v[220:221], 12, v[220:221]
	s_cbranch_vccnz .LBB0_765
	s_ashr_i32 s65, s64, 31
	s_lshl_b64 s[0:1], s[64:65], 21
	s_add_u32 s0, s77, s0
	s_addc_u32 s1, s78, s1
	v_ashrrev_i32_e32 v159, 31, v158
	v_lshl_add_u64 v[198:199], s[0:1], 0, v[220:221]
	v_lshl_add_u64 v[198:199], v[158:159], 1, v[198:199]
	v_add_co_u32_e32 v198, vcc, 0xfe000000, v198
	s_mov_b64 s[30:31], 0
	s_nop 0
	v_addc_co_u32_e32 v199, vcc, -1, v199, vcc
	v_cvt_pk_bf16_f32 v238, v149, v179
	v_cvt_pk_bf16_f32 v239, v189, v213
	v_cvt_pk_bf16_f32 v240, v3, v157
	v_cvt_pk_bf16_f32 v241, v169, v203
	global_store_dwordx4 v[198:199], v[238:241], off

.LBB0_770:
	v_ashrrev_i32_e32 v213, 31, v212
	s_waitcnt vmcnt(13)
	v_cvt_f32_ubyte1_e32 v227, v224
	v_cvt_f32_ubyte0_e32 v226, v224
	v_cvt_f32_ubyte3_e32 v229, v224
	v_cvt_f32_ubyte2_e32 v228, v224
	v_cvt_f32_ubyte1_e32 v221, v225
	v_cvt_f32_ubyte0_e32 v220, v225
	v_cvt_f32_ubyte3_e32 v223, v225
	v_cvt_f32_ubyte2_e32 v222, v225
	s_and_b64 vcc, exec, s[12:13]
	s_mov_b64 s[30:31], -1
	s_cbranch_vccnz .LBB0_776
	v_mul_f32_e32 v3, 0x3b808081, v226
	v_mul_f32_e32 v157, 0x3b808081, v227
	v_mul_f32_e32 v159, 0x3b808081, v228
	v_mul_f32_e32 v189, 0x3b808081, v229
	v_mul_f32_e32 v149, v122, v3
	v_mul_f32_e32 v3, 0x3b808081, v220
	v_mul_f32_e32 v169, v123, v157
	v_mul_f32_e32 v157, 0x3b808081, v221
	v_mul_f32_e32 v179, v124, v159
	v_mul_f32_e32 v159, 0x3b808081, v222
	v_mul_f32_e32 v203, v125, v189
	v_mul_f32_e32 v189, 0x3b808081, v223
	v_mul_f32_e32 v3, v118, v3
	v_mul_f32_e32 v157, v119, v157
	v_mul_f32_e32 v159, v120, v159
	v_mul_f32_e32 v189, v121, v189
	s_and_b64 vcc, exec, s[14:15]
	s_cbranch_vccnz .LBB0_773
	s_ashr_i32 s65, s64, 31
	s_lshl_b64 s[0:1], s[64:65], 21
	s_add_u32 s0, s77, s0
	s_addc_u32 s1, s78, s1
	v_lshlrev_b64 v[198:199], 12, v[212:213]
	v_lshl_add_u64 v[198:199], s[0:1], 0, v[198:199]
	v_lshl_add_u64 v[198:199], v[4:5], 1, v[198:199]
	v_add_co_u32_e32 v198, vcc, 0xfe000000, v198
	s_mov_b64 s[30:31], 0
	s_nop 0
	v_addc_co_u32_e32 v199, vcc, -1, v199, vcc
	v_cvt_pk_bf16_f32 v230, v149, v169
	v_cvt_pk_bf16_f32 v231, v179, v203
	v_cvt_pk_bf16_f32 v232, v3, v157
	v_cvt_pk_bf16_f32 v233, v159, v189
	global_store_dwordx4 v[198:199], v[230:233], off

.LBB0_778:
	s_waitcnt vmcnt(12)
	v_cvt_f32_ubyte1_e32 v223, v218
	v_cvt_f32_ubyte0_e32 v222, v218
	v_cvt_f32_ubyte3_e32 v225, v218
	v_cvt_f32_ubyte2_e32 v224, v218
	v_cvt_f32_ubyte1_e32 v217, v219
	v_cvt_f32_ubyte0_e32 v216, v219
	v_cvt_f32_ubyte3_e32 v221, v219
	v_cvt_f32_ubyte2_e32 v220, v219
	s_and_b64 vcc, exec, s[12:13]
	s_mov_b64 s[30:31], -1
	s_cbranch_vccnz .LBB0_784
	v_mul_f32_e32 v159, 0x3b808081, v224
	v_mul_f32_e32 v189, v92, v159
	v_mul_f32_e32 v159, 0x3b808081, v220
	v_mul_f32_e32 v3, 0x3b808081, v222
	v_mul_f32_e32 v157, 0x3b808081, v223
	v_mul_f32_e32 v169, v88, v159
	v_mul_f32_e32 v159, 0x3b808081, v225
	v_mul_f32_e32 v149, v90, v3
	v_mul_f32_e32 v3, 0x3b808081, v216
	v_mul_f32_e32 v179, v91, v157
	v_mul_f32_e32 v157, 0x3b808081, v217
	v_mul_f32_e32 v218, v93, v159
	v_mul_f32_e32 v159, 0x3b808081, v221
	v_mul_f32_e32 v3, v86, v3
	v_mul_f32_e32 v157, v87, v157
	v_mul_f32_e32 v203, v89, v159
	s_and_b64 vcc, exec, s[14:15]
	v_lshlrev_b64 v[212:213], 12, v[212:213]
	s_cbranch_vccnz .LBB0_781
	s_ashr_i32 s65, s64, 31
	s_lshl_b64 s[0:1], s[64:65], 21
	s_add_u32 s0, s77, s0
	s_addc_u32 s1, s78, s1
	v_ashrrev_i32_e32 v159, 31, v158
	v_lshl_add_u64 v[198:199], s[0:1], 0, v[212:213]
	v_lshl_add_u64 v[198:199], v[158:159], 1, v[198:199]
	v_add_co_u32_e32 v198, vcc, 0xfe000000, v198
	s_mov_b64 s[30:31], 0
	s_nop 0
	v_addc_co_u32_e32 v199, vcc, -1, v199, vcc
	v_cvt_pk_bf16_f32 v226, v149, v179
	v_cvt_pk_bf16_f32 v227, v189, v218
	v_cvt_pk_bf16_f32 v228, v3, v157
	v_cvt_pk_bf16_f32 v229, v169, v203
	global_store_dwordx4 v[198:199], v[226:229], off

.LBB0_786:
	v_ashrrev_i32_e32 v203, 31, v202
	s_waitcnt vmcnt(11)
	v_cvt_f32_ubyte1_e32 v217, v214
	v_cvt_f32_ubyte0_e32 v216, v214
	v_cvt_f32_ubyte3_e32 v219, v214
	v_cvt_f32_ubyte2_e32 v218, v214
	v_cvt_f32_ubyte1_e32 v211, v215
	v_cvt_f32_ubyte0_e32 v210, v215
	v_cvt_f32_ubyte3_e32 v213, v215
	v_cvt_f32_ubyte2_e32 v212, v215
	s_and_b64 vcc, exec, s[12:13]
	s_mov_b64 s[30:31], -1
	s_cbranch_vccnz .LBB0_792
	v_mul_f32_e32 v3, 0x3b808081, v216
	v_mul_f32_e32 v157, 0x3b808081, v217
	v_mul_f32_e32 v159, 0x3b808081, v218
	v_mul_f32_e32 v189, 0x3b808081, v219
	v_mul_f32_e32 v149, v114, v3
	v_mul_f32_e32 v3, 0x3b808081, v210
	v_mul_f32_e32 v169, v115, v157
	v_mul_f32_e32 v157, 0x3b808081, v211
	v_mul_f32_e32 v179, v116, v159
	v_mul_f32_e32 v159, 0x3b808081, v212
	v_mul_f32_e32 v214, v117, v189
	v_mul_f32_e32 v189, 0x3b808081, v213
	v_mul_f32_e32 v3, v110, v3
	v_mul_f32_e32 v157, v111, v157
	v_mul_f32_e32 v159, v112, v159
	v_mul_f32_e32 v189, v113, v189
	s_and_b64 vcc, exec, s[14:15]
	s_cbranch_vccnz .LBB0_789
	s_ashr_i32 s65, s64, 31
	s_lshl_b64 s[0:1], s[64:65], 21
	s_add_u32 s0, s77, s0
	s_addc_u32 s1, s78, s1
	v_lshlrev_b64 v[198:199], 12, v[202:203]
	v_lshl_add_u64 v[198:199], s[0:1], 0, v[198:199]
	v_lshl_add_u64 v[198:199], v[4:5], 1, v[198:199]
	v_add_co_u32_e32 v198, vcc, 0xfe000000, v198
	s_mov_b64 s[30:31], 0
	s_nop 0
	v_addc_co_u32_e32 v199, vcc, -1, v199, vcc
	v_cvt_pk_bf16_f32 v220, v149, v169
	v_cvt_pk_bf16_f32 v221, v179, v214
	v_cvt_pk_bf16_f32 v222, v3, v157
	v_cvt_pk_bf16_f32 v223, v159, v189
	global_store_dwordx4 v[198:199], v[220:223], off

.LBB0_794:
	s_waitcnt vmcnt(10)
	v_cvt_f32_ubyte1_e32 v213, v208
	v_cvt_f32_ubyte0_e32 v212, v208
	v_cvt_f32_ubyte3_e32 v215, v208
	v_cvt_f32_ubyte2_e32 v214, v208
	v_cvt_f32_ubyte1_e32 v207, v209
	v_cvt_f32_ubyte0_e32 v206, v209
	v_cvt_f32_ubyte3_e32 v211, v209
	v_cvt_f32_ubyte2_e32 v210, v209
	s_and_b64 vcc, exec, s[12:13]
	s_mov_b64 s[30:31], -1
	s_cbranch_vccnz .LBB0_800
	v_mul_f32_e32 v159, 0x3b808081, v214
	v_mul_f32_e32 v189, v84, v159
	v_mul_f32_e32 v159, 0x3b808081, v210
	v_mul_f32_e32 v3, 0x3b808081, v212
	v_mul_f32_e32 v157, 0x3b808081, v213
	v_mul_f32_e32 v169, v80, v159
	v_mul_f32_e32 v159, 0x3b808081, v215
	v_mul_f32_e32 v149, v82, v3
	v_mul_f32_e32 v3, 0x3b808081, v206
	v_mul_f32_e32 v179, v83, v157
	v_mul_f32_e32 v157, 0x3b808081, v207
	v_mul_f32_e32 v209, v85, v159
	v_mul_f32_e32 v159, 0x3b808081, v211
	v_mul_f32_e32 v3, v78, v3
	v_mul_f32_e32 v157, v79, v157
	v_mul_f32_e32 v208, v81, v159
	s_and_b64 vcc, exec, s[14:15]
	v_lshlrev_b64 v[202:203], 12, v[202:203]
	s_cbranch_vccnz .LBB0_797
	s_ashr_i32 s65, s64, 31
	s_lshl_b64 s[0:1], s[64:65], 21
	s_add_u32 s0, s77, s0
	s_addc_u32 s1, s78, s1
	v_ashrrev_i32_e32 v159, 31, v158
	v_lshl_add_u64 v[198:199], s[0:1], 0, v[202:203]
	v_lshl_add_u64 v[198:199], v[158:159], 1, v[198:199]
	v_add_co_u32_e32 v198, vcc, 0xfe000000, v198
	s_mov_b64 s[30:31], 0
	s_nop 0
	v_addc_co_u32_e32 v199, vcc, -1, v199, vcc
	v_cvt_pk_bf16_f32 v216, v149, v179
	v_cvt_pk_bf16_f32 v217, v189, v209
	v_cvt_pk_bf16_f32 v218, v3, v157
	v_cvt_pk_bf16_f32 v219, v169, v208
	global_store_dwordx4 v[198:199], v[216:219], off

.LBB0_802:
	v_ashrrev_i32_e32 v189, 31, v188
	s_waitcnt vmcnt(9)
	v_cvt_f32_ubyte1_e32 v207, v204
	v_cvt_f32_ubyte0_e32 v206, v204
	v_cvt_f32_ubyte3_e32 v209, v204
	v_cvt_f32_ubyte2_e32 v208, v204
	v_cvt_f32_ubyte1_e32 v201, v205
	v_cvt_f32_ubyte0_e32 v200, v205
	v_cvt_f32_ubyte3_e32 v203, v205
	v_cvt_f32_ubyte2_e32 v202, v205
	s_and_b64 vcc, exec, s[12:13]
	s_mov_b64 s[30:31], -1
	s_cbranch_vccnz .LBB0_808
	v_mul_f32_e32 v3, 0x3b808081, v206
	v_mul_f32_e32 v157, 0x3b808081, v207
	v_mul_f32_e32 v159, 0x3b808081, v208
	v_mul_f32_e32 v198, 0x3b808081, v209
	v_mul_f32_e32 v149, v106, v3
	v_mul_f32_e32 v3, 0x3b808081, v200
	v_mul_f32_e32 v169, v107, v157
	v_mul_f32_e32 v157, 0x3b808081, v201
	v_mul_f32_e32 v179, v108, v159
	v_mul_f32_e32 v159, 0x3b808081, v202
	v_mul_f32_e32 v205, v109, v198
	v_mul_f32_e32 v198, 0x3b808081, v203
	v_mul_f32_e32 v3, v102, v3
	v_mul_f32_e32 v157, v103, v157
	v_mul_f32_e32 v159, v104, v159
	v_mul_f32_e32 v204, v105, v198
	s_and_b64 vcc, exec, s[14:15]
	s_cbranch_vccnz .LBB0_805
	s_ashr_i32 s65, s64, 31
	s_lshl_b64 s[0:1], s[64:65], 21
	s_add_u32 s0, s77, s0
	s_addc_u32 s1, s78, s1
	v_lshlrev_b64 v[198:199], 12, v[188:189]
	v_lshl_add_u64 v[198:199], s[0:1], 0, v[198:199]
	v_lshl_add_u64 v[198:199], v[4:5], 1, v[198:199]
	v_add_co_u32_e32 v198, vcc, 0xfe000000, v198
	s_mov_b64 s[30:31], 0
	s_nop 0
	v_addc_co_u32_e32 v199, vcc, -1, v199, vcc
	v_cvt_pk_bf16_f32 v210, v149, v169
	v_cvt_pk_bf16_f32 v211, v179, v205
	v_cvt_pk_bf16_f32 v212, v3, v157
	v_cvt_pk_bf16_f32 v213, v159, v204
	global_store_dwordx4 v[198:199], v[210:213], off

.LBB0_810:
	s_waitcnt vmcnt(8)
	v_cvt_f32_ubyte1_e32 v203, v194
	v_cvt_f32_ubyte0_e32 v202, v194
	v_cvt_f32_ubyte3_e32 v205, v194
	v_cvt_f32_ubyte2_e32 v204, v194
	v_cvt_f32_ubyte1_e32 v193, v195
	v_cvt_f32_ubyte0_e32 v192, v195
	v_cvt_f32_ubyte3_e32 v201, v195
	v_cvt_f32_ubyte2_e32 v200, v195
	s_and_b64 vcc, exec, s[12:13]
	s_mov_b64 s[30:31], -1
	s_cbranch_vccnz .LBB0_816
	v_mul_f32_e32 v159, 0x3b808081, v204
	v_mul_f32_e32 v194, v76, v159
	v_mul_f32_e32 v159, 0x3b808081, v200
	v_mul_f32_e32 v3, 0x3b808081, v202
	v_mul_f32_e32 v157, 0x3b808081, v203
	v_mul_f32_e32 v169, v72, v159
	v_mul_f32_e32 v159, 0x3b808081, v205
	v_mul_f32_e32 v149, v74, v3
	v_mul_f32_e32 v3, 0x3b808081, v192
	v_mul_f32_e32 v179, v75, v157
	v_mul_f32_e32 v157, 0x3b808081, v193
	v_mul_f32_e32 v206, v77, v159
	v_mul_f32_e32 v159, 0x3b808081, v201
	v_mul_f32_e32 v3, v70, v3
	v_mul_f32_e32 v157, v71, v157
	v_mul_f32_e32 v195, v73, v159
	s_and_b64 vcc, exec, s[14:15]
	v_lshlrev_b64 v[188:189], 12, v[188:189]
	s_cbranch_vccnz .LBB0_813
	s_ashr_i32 s65, s64, 31
	s_lshl_b64 s[0:1], s[64:65], 21
	s_add_u32 s0, s77, s0
	s_addc_u32 s1, s78, s1
	v_ashrrev_i32_e32 v159, 31, v158
	v_lshl_add_u64 v[198:199], s[0:1], 0, v[188:189]
	v_lshl_add_u64 v[198:199], v[158:159], 1, v[198:199]
	v_add_co_u32_e32 v198, vcc, 0xfe000000, v198
	s_mov_b64 s[30:31], 0
	s_nop 0
	v_addc_co_u32_e32 v199, vcc, -1, v199, vcc
	v_cvt_pk_bf16_f32 v208, v149, v179
	v_cvt_pk_bf16_f32 v209, v194, v206
	v_cvt_pk_bf16_f32 v210, v3, v157
	v_cvt_pk_bf16_f32 v211, v169, v195
	global_store_dwordx4 v[198:199], v[208:211], off
